# NSA tile loops: 32-term probability sum as a packed-f32 add tree (17 instructions instead of 33) in the selected and sliding-window loops
# speedup vs baseline: 1.0086x; 1.0086x over previous
; __device__ __forceinline__ void nsa_softmax_pv(NsaSm& st, f32x16& p0, f32x16& p1, const LAS unsigned char* vslot, LAS float* wsf, int lane, int r32, int hi, bool on = true) {
;     const float rmx = rowmax32(p0, p1); const float rm = on ? rmx : SNEG; const float mn = fmaxf(st.m, rm); const float f = __builtin_amdgcn_exp2f(st.m - mn); st.m = mn;
;     const float cs = on ? mn : 1.0e30f;
;     float s = 0.f;
; #pragma unroll
;     for (int r = 0; r < 16; ++r) { p0[r] = __builtin_amdgcn_exp2f(p0[r] - cs); p1[r] = __builtin_amdgcn_exp2f(p1[r] - cs); s += p0[r] + p1[r]; }
;     st.l = st.l * f + s;
.LBB0_1335:
	v_pk_add_f32 v[8:9], v[8:9], v[10:11]
	v_pk_add_f32 v[12:13], v[12:13], v[14:15]
	v_pk_add_f32 v[80:81], v[80:81], v[82:83]
	v_pk_add_f32 v[84:85], v[84:85], v[86:87]
	v_pk_add_f32 v[88:89], v[88:89], v[90:91]
	v_pk_add_f32 v[92:93], v[92:93], v[94:95]
	v_pk_add_f32 v[96:97], v[96:97], v[98:99]
	v_add_f32_e32 v2, v7, v102
	v_pk_add_f32 v[8:9], v[8:9], v[12:13]
	v_pk_add_f32 v[80:81], v[80:81], v[84:85]
	v_pk_add_f32 v[88:89], v[88:89], v[92:93]
	v_pk_add_f32 v[96:97], v[96:97], v[100:101]
	v_pk_add_f32 v[8:9], v[8:9], v[80:81]
	v_pk_add_f32 v[88:89], v[88:89], v[96:97]
	v_pk_add_f32 v[8:9], v[8:9], v[88:89]
	v_add_f32_e32 v3, v8, v9
	v_add_f32_e32 v2, v2, v3
	v_fmac_f32_e32 v2, v157, v6
	s_andn2_b64 vcc, exec, s[6:7]
	s_xor_b32 s42, s42, 1
	s_waitcnt lgkmcnt(0)
	s_barrier
	s_cbranch_vccz .LBB0_1337
	v_mov_b32_e32 v157, v2
	v_mov_b32_e32 v158, v0
	s_mov_b32 s8, s43
	s_mov_b64 s[2:3], s[4:5]
	s_branch .LBB0_1323

; #define NSA_STORET(slot_) do { *(LAS u32x4*)(lds + NL_KS + (slot_) * 8192 + wid * 1024 + lane * 16) = kreg; *(LAS u32x4*)(lds + NL_VS + (slot_) * 8192 + wid * 1024 + lane * 16) = vreg; } while (0)
; __device__ __forceinline__ void nsa_softmax_pv(NsaSm& st, f32x16& p0, f32x16& p1, const LAS unsigned char* vslot, LAS float* wsf, int lane, int r32, int hi, bool on = true) {
;     const float rmx = rowmax32(p0, p1); const float rm = on ? rmx : SNEG; const float mn = fmaxf(st.m, rm); const float f = __builtin_amdgcn_exp2f(st.m - mn); st.m = mn;
;     const float cs = on ? mn : 1.0e30f;
;     float s = 0.f;
; #pragma unroll
;     for (int r = 0; r < 16; ++r) { p0[r] = __builtin_amdgcn_exp2f(p0[r] - cs); p1[r] = __builtin_amdgcn_exp2f(p1[r] - cs); s += p0[r] + p1[r]; }
;     st.l = st.l * f + s;
; __device__ __forceinline__ void nsa_unit(const Ctx& c, int l, int b, int n, int qt) {
;     ...
;             nsa_softmax_pv(st, p0, p1, lds + NL_VS + cur * 8192, wsf, lane, r32, hi);
;             if (more) NSA_STORET(cur ^ 1);
;             __syncthreads();
;             if (!more) break;
.LBB0_1352:
	v_pk_add_f32 v[4:5], v[4:5], v[6:7]
	v_pk_add_f32 v[8:9], v[8:9], v[10:11]
	v_pk_add_f32 v[12:13], v[12:13], v[14:15]
	v_pk_add_f32 v[112:113], v[112:113], v[114:115]
	v_pk_add_f32 v[116:117], v[116:117], v[118:119]
	v_pk_add_f32 v[120:121], v[120:121], v[122:123]
	v_pk_add_f32 v[124:125], v[124:125], v[126:127]
	v_add_f32_e32 v3, v3, v130
	v_pk_add_f32 v[4:5], v[4:5], v[8:9]
	v_pk_add_f32 v[12:13], v[12:13], v[112:113]
	v_pk_add_f32 v[116:117], v[116:117], v[120:121]
	v_pk_add_f32 v[124:125], v[124:125], v[128:129]
	v_pk_add_f32 v[4:5], v[4:5], v[12:13]
	v_pk_add_f32 v[116:117], v[116:117], v[124:125]
	v_pk_add_f32 v[4:5], v[4:5], v[116:117]
	v_add_f32_e32 v4, v4, v5
	v_add_f32_e32 v3, v3, v4
	s_xor_b32 s25, s25, 1
	s_add_i32 s13, s13, -1
	s_add_i32 s24, s24, 64
	v_fmac_f32_e32 v3, v250, v2
	s_cmp_gt_i32 s19, s20
	s_waitcnt lgkmcnt(0)
	s_barrier
	s_cbranch_scc0 .LBB0_1354
	v_mov_b32_e32 v250, v3
	v_mov_b32_e32 v233, v0
	s_branch .LBB0_1340
